# fused-norm epilogues (w_out, FF2): second-half gain loads issued ahead of the first half's stores, so their wait no longer drains those stores mid-epilogue (in-order vmcnt)
# speedup vs baseline: 1.0039x; 1.0039x over previous
.LBB0_719:
	s_or_b64 exec, exec, s[52:53]
	v_lshlrev_b64 v[204:205], 2, v[200:201]
	s_waitcnt lgkmcnt(0)
	s_barrier
	v_lshl_add_u64 v[206:207], s[20:21], 0, v[204:205]
	global_load_dwordx4 v[196:199], v[206:207], off
	global_load_dwordx4 v[192:195], v[206:207], off offset:16
	global_load_dwordx4 v[226:229], v[206:207], off offset:512
	global_load_dwordx4 v[230:233], v[206:207], off offset:528
	v_add_u32_e32 v236, s27, v210
	v_lshlrev_b32_e32 v236, 12, v236
	v_add_u32_e32 v236, v236, v204
	v_lshl_add_u32 v209, v210, 2, 0
	ds_read_b32 v214, v209 offset:8192
	s_waitcnt lgkmcnt(0)
	v_pk_mul_f32 v[116:117], v[116:117], v[214:215] op_sel_hi:[1,0]
	v_pk_mul_f32 v[118:119], v[118:119], v[214:215] op_sel_hi:[1,0]
	v_pk_mul_f32 v[216:217], v[112:113], v[214:215] op_sel_hi:[1,0]
	v_pk_mul_f32 v[214:215], v[114:115], v[214:215] op_sel_hi:[1,0]
	s_waitcnt vmcnt(2)
	v_pk_fma_f32 v[114:115], v[198:199], v[118:119], v[190:191]
	v_pk_fma_f32 v[112:113], v[196:197], v[116:117], v[188:189]
	v_pk_fma_f32 v[118:119], v[194:195], v[214:215], v[186:187]
	v_pk_fma_f32 v[116:117], v[192:193], v[216:217], v[184:185]
	global_load_dwordx4 v[184:187], v236, s[48:49] offset:512
	global_load_dwordx4 v[188:191], v236, s[48:49] offset:528
	ds_read_b32 v234, v209 offset:8256
	s_waitcnt lgkmcnt(0)
	v_pk_mul_f32 v[124:125], v[124:125], v[234:235] op_sel_hi:[1,0]
	v_pk_mul_f32 v[126:127], v[126:127], v[234:235] op_sel_hi:[1,0]
	v_pk_mul_f32 v[238:239], v[120:121], v[234:235] op_sel_hi:[1,0]
	v_pk_mul_f32 v[234:235], v[122:123], v[234:235] op_sel_hi:[1,0]
	v_pk_fma_f32 v[122:123], v[198:199], v[126:127], v[182:183]
	v_pk_fma_f32 v[120:121], v[196:197], v[124:125], v[180:181]
	v_pk_fma_f32 v[126:127], v[194:195], v[234:235], v[178:179]
	v_pk_fma_f32 v[124:125], v[192:193], v[238:239], v[176:177]
	v_add_u32_e32 v237, 0x10000, v236
	global_load_dwordx4 v[176:179], v237, s[48:49] offset:512
	global_load_dwordx4 v[180:183], v237, s[48:49] offset:528
	ds_read_b32 v234, v209 offset:8320
	s_waitcnt lgkmcnt(0)
	v_pk_mul_f32 v[108:109], v[108:109], v[234:235] op_sel_hi:[1,0]
	v_pk_mul_f32 v[110:111], v[110:111], v[234:235] op_sel_hi:[1,0]
	v_pk_mul_f32 v[238:239], v[104:105], v[234:235] op_sel_hi:[1,0]
	v_pk_mul_f32 v[234:235], v[106:107], v[234:235] op_sel_hi:[1,0]
	v_pk_fma_f32 v[106:107], v[198:199], v[110:111], v[174:175]
	v_pk_fma_f32 v[104:105], v[196:197], v[108:109], v[172:173]
	v_pk_fma_f32 v[110:111], v[194:195], v[234:235], v[170:171]
	v_pk_fma_f32 v[108:109], v[192:193], v[238:239], v[168:169]
	v_add_u32_e32 v237, 0x20000, v236
	global_load_dwordx4 v[168:171], v237, s[48:49] offset:512
	global_load_dwordx4 v[172:175], v237, s[48:49] offset:528
	ds_read_b32 v234, v209 offset:8384
	s_waitcnt lgkmcnt(0)
	v_pk_mul_f32 v[100:101], v[100:101], v[234:235] op_sel_hi:[1,0]
	v_pk_mul_f32 v[102:103], v[102:103], v[234:235] op_sel_hi:[1,0]
	v_pk_mul_f32 v[96:97], v[96:97], v[234:235] op_sel_hi:[1,0]
	v_pk_mul_f32 v[98:99], v[98:99], v[234:235] op_sel_hi:[1,0]
	v_pk_fma_f32 v[102:103], v[198:199], v[102:103], v[166:167]
	v_pk_fma_f32 v[100:101], v[196:197], v[100:101], v[164:165]
	v_pk_fma_f32 v[98:99], v[194:195], v[98:99], v[162:163]
	v_pk_fma_f32 v[96:97], v[192:193], v[96:97], v[160:161]
	v_add_u32_e32 v237, 0x30000, v236
	global_load_dwordx4 v[160:163], v237, s[48:49] offset:512
	global_load_dwordx4 v[164:167], v237, s[48:49] offset:528
	ds_read_b32 v234, v209 offset:8704
	s_waitcnt lgkmcnt(0)
	v_pk_mul_f32 v[92:93], v[92:93], v[234:235] op_sel_hi:[1,0]
	v_pk_mul_f32 v[94:95], v[94:95], v[234:235] op_sel_hi:[1,0]
	v_pk_mul_f32 v[88:89], v[88:89], v[234:235] op_sel_hi:[1,0]
	v_pk_mul_f32 v[90:91], v[90:91], v[234:235] op_sel_hi:[1,0]
	v_pk_fma_f32 v[94:95], v[198:199], v[94:95], v[158:159]
	v_pk_fma_f32 v[92:93], v[196:197], v[92:93], v[156:157]
	v_pk_fma_f32 v[90:91], v[194:195], v[90:91], v[154:155]
	v_pk_fma_f32 v[88:89], v[192:193], v[88:89], v[152:153]
	v_add_u32_e32 v237, 0x80000, v236
	global_load_dwordx4 v[152:155], v237, s[48:49] offset:512
	global_load_dwordx4 v[156:159], v237, s[48:49] offset:528
	ds_read_b32 v234, v209 offset:8768
	s_waitcnt lgkmcnt(0)
	v_pk_mul_f32 v[84:85], v[84:85], v[234:235] op_sel_hi:[1,0]
	v_pk_mul_f32 v[86:87], v[86:87], v[234:235] op_sel_hi:[1,0]
	v_pk_mul_f32 v[80:81], v[80:81], v[234:235] op_sel_hi:[1,0]
	v_pk_mul_f32 v[82:83], v[82:83], v[234:235] op_sel_hi:[1,0]
	v_pk_fma_f32 v[86:87], v[198:199], v[86:87], v[150:151]
	v_pk_fma_f32 v[84:85], v[196:197], v[84:85], v[148:149]
	v_pk_fma_f32 v[82:83], v[194:195], v[82:83], v[146:147]
	v_pk_fma_f32 v[80:81], v[192:193], v[80:81], v[144:145]
	v_add_u32_e32 v237, 0x90000, v236
	global_load_dwordx4 v[144:147], v237, s[48:49] offset:512
	global_load_dwordx4 v[148:151], v237, s[48:49] offset:528
	ds_read_b32 v234, v209 offset:8832
	s_waitcnt lgkmcnt(0)
	v_pk_mul_f32 v[76:77], v[76:77], v[234:235] op_sel_hi:[1,0]
	v_pk_mul_f32 v[78:79], v[78:79], v[234:235] op_sel_hi:[1,0]
	v_pk_mul_f32 v[72:73], v[72:73], v[234:235] op_sel_hi:[1,0]
	v_pk_mul_f32 v[74:75], v[74:75], v[234:235] op_sel_hi:[1,0]
	v_pk_fma_f32 v[78:79], v[198:199], v[78:79], v[142:143]
	v_pk_fma_f32 v[76:77], v[196:197], v[76:77], v[140:141]
	v_pk_fma_f32 v[74:75], v[194:195], v[74:75], v[138:139]
	v_pk_fma_f32 v[72:73], v[192:193], v[72:73], v[136:137]
	v_add_u32_e32 v237, 0xa0000, v236
	global_load_dwordx4 v[136:139], v237, s[48:49] offset:512
	global_load_dwordx4 v[140:143], v237, s[48:49] offset:528
	ds_read_b32 v234, v209 offset:8896
	s_waitcnt lgkmcnt(0)
	v_pk_mul_f32 v[68:69], v[68:69], v[234:235] op_sel_hi:[1,0]
	v_pk_mul_f32 v[70:71], v[70:71], v[234:235] op_sel_hi:[1,0]
	v_pk_mul_f32 v[64:65], v[64:65], v[234:235] op_sel_hi:[1,0]
	v_pk_mul_f32 v[66:67], v[66:67], v[234:235] op_sel_hi:[1,0]
	v_pk_fma_f32 v[70:71], v[198:199], v[70:71], v[134:135]
	v_pk_fma_f32 v[68:69], v[196:197], v[68:69], v[132:133]
	v_pk_fma_f32 v[66:67], v[194:195], v[66:67], v[130:131]
	v_pk_fma_f32 v[64:65], v[192:193], v[64:65], v[128:129]
	v_add_u32_e32 v237, 0xb0000, v236
	global_load_dwordx4 v[128:131], v237, s[48:49] offset:512
	global_load_dwordx4 v[132:135], v237, s[48:49] offset:528
	ds_read_b32 v234, v209 offset:8192
	s_waitcnt lgkmcnt(0)
	v_pk_mul_f32 v[60:61], v[60:61], v[234:235] op_sel_hi:[1,0]
	v_pk_mul_f32 v[62:63], v[62:63], v[234:235] op_sel_hi:[1,0]
	v_pk_mul_f32 v[56:57], v[56:57], v[234:235] op_sel_hi:[1,0]
	v_pk_mul_f32 v[58:59], v[58:59], v[234:235] op_sel_hi:[1,0]
	s_waitcnt vmcnt(14)
	v_pk_fma_f32 v[62:63], v[228:229], v[62:63], v[186:187]
	v_pk_fma_f32 v[60:61], v[226:227], v[60:61], v[184:185]
	v_pk_fma_f32 v[58:59], v[232:233], v[58:59], v[190:191]
	v_pk_fma_f32 v[56:57], v[230:231], v[56:57], v[188:189]
	ds_read_b32 v234, v209 offset:8256
	s_waitcnt lgkmcnt(0)
	v_pk_mul_f32 v[52:53], v[52:53], v[234:235] op_sel_hi:[1,0]
	v_pk_mul_f32 v[54:55], v[54:55], v[234:235] op_sel_hi:[1,0]
	v_pk_mul_f32 v[48:49], v[48:49], v[234:235] op_sel_hi:[1,0]
	v_pk_mul_f32 v[50:51], v[50:51], v[234:235] op_sel_hi:[1,0]
	s_waitcnt vmcnt(12)
	v_pk_fma_f32 v[54:55], v[228:229], v[54:55], v[178:179]
	v_pk_fma_f32 v[52:53], v[226:227], v[52:53], v[176:177]
	v_pk_fma_f32 v[50:51], v[232:233], v[50:51], v[182:183]
	v_pk_fma_f32 v[48:49], v[230:231], v[48:49], v[180:181]
	ds_read_b32 v234, v209 offset:8320
	s_waitcnt lgkmcnt(0)
	v_pk_mul_f32 v[44:45], v[44:45], v[234:235] op_sel_hi:[1,0]
	v_pk_mul_f32 v[46:47], v[46:47], v[234:235] op_sel_hi:[1,0]
	v_pk_mul_f32 v[40:41], v[40:41], v[234:235] op_sel_hi:[1,0]
	v_pk_mul_f32 v[42:43], v[42:43], v[234:235] op_sel_hi:[1,0]
	s_waitcnt vmcnt(10)
	v_pk_fma_f32 v[46:47], v[228:229], v[46:47], v[170:171]
	v_pk_fma_f32 v[44:45], v[226:227], v[44:45], v[168:169]
	v_pk_fma_f32 v[42:43], v[232:233], v[42:43], v[174:175]
	v_pk_fma_f32 v[40:41], v[230:231], v[40:41], v[172:173]
	ds_read_b32 v234, v209 offset:8384
	s_waitcnt lgkmcnt(0)
	v_pk_mul_f32 v[36:37], v[36:37], v[234:235] op_sel_hi:[1,0]
	v_pk_mul_f32 v[38:39], v[38:39], v[234:235] op_sel_hi:[1,0]
	v_pk_mul_f32 v[32:33], v[32:33], v[234:235] op_sel_hi:[1,0]
	v_pk_mul_f32 v[34:35], v[34:35], v[234:235] op_sel_hi:[1,0]
	s_waitcnt vmcnt(8)
	v_pk_fma_f32 v[38:39], v[228:229], v[38:39], v[162:163]
	v_pk_fma_f32 v[36:37], v[226:227], v[36:37], v[160:161]
	v_pk_fma_f32 v[34:35], v[232:233], v[34:35], v[166:167]
	v_pk_fma_f32 v[32:33], v[230:231], v[32:33], v[164:165]
	ds_read_b32 v234, v209 offset:8704
	s_waitcnt lgkmcnt(0)
	v_pk_mul_f32 v[28:29], v[28:29], v[234:235] op_sel_hi:[1,0]
	v_pk_mul_f32 v[30:31], v[30:31], v[234:235] op_sel_hi:[1,0]
	v_pk_mul_f32 v[24:25], v[24:25], v[234:235] op_sel_hi:[1,0]
	v_pk_mul_f32 v[26:27], v[26:27], v[234:235] op_sel_hi:[1,0]
	s_waitcnt vmcnt(6)
	v_pk_fma_f32 v[30:31], v[228:229], v[30:31], v[154:155]
	v_pk_fma_f32 v[28:29], v[226:227], v[28:29], v[152:153]
	v_pk_fma_f32 v[26:27], v[232:233], v[26:27], v[158:159]
	v_pk_fma_f32 v[24:25], v[230:231], v[24:25], v[156:157]
	ds_read_b32 v234, v209 offset:8768
	s_waitcnt lgkmcnt(0)
	v_pk_mul_f32 v[20:21], v[20:21], v[234:235] op_sel_hi:[1,0]
	v_pk_mul_f32 v[22:23], v[22:23], v[234:235] op_sel_hi:[1,0]
	v_pk_mul_f32 v[16:17], v[16:17], v[234:235] op_sel_hi:[1,0]
	v_pk_mul_f32 v[18:19], v[18:19], v[234:235] op_sel_hi:[1,0]
	s_waitcnt vmcnt(4)
	v_pk_fma_f32 v[22:23], v[228:229], v[22:23], v[146:147]
	v_pk_fma_f32 v[20:21], v[226:227], v[20:21], v[144:145]
	v_pk_fma_f32 v[18:19], v[232:233], v[18:19], v[150:151]
	v_pk_fma_f32 v[16:17], v[230:231], v[16:17], v[148:149]
	ds_read_b32 v234, v209 offset:8832
	s_waitcnt lgkmcnt(0)
	v_pk_mul_f32 v[12:13], v[12:13], v[234:235] op_sel_hi:[1,0]
	v_pk_mul_f32 v[14:15], v[14:15], v[234:235] op_sel_hi:[1,0]
	v_pk_mul_f32 v[8:9], v[8:9], v[234:235] op_sel_hi:[1,0]
	v_pk_mul_f32 v[10:11], v[10:11], v[234:235] op_sel_hi:[1,0]
	s_waitcnt vmcnt(2)
	v_pk_fma_f32 v[14:15], v[228:229], v[14:15], v[138:139]
	v_pk_fma_f32 v[12:13], v[226:227], v[12:13], v[136:137]
	v_pk_fma_f32 v[10:11], v[232:233], v[10:11], v[142:143]
	v_pk_fma_f32 v[8:9], v[230:231], v[8:9], v[140:141]
	ds_read_b32 v234, v209 offset:8896
	s_waitcnt lgkmcnt(0)
	v_pk_mul_f32 v[4:5], v[4:5], v[234:235] op_sel_hi:[1,0]
	v_pk_mul_f32 v[6:7], v[6:7], v[234:235] op_sel_hi:[1,0]
	v_pk_mul_f32 v[0:1], v[0:1], v[234:235] op_sel_hi:[1,0]
	v_pk_mul_f32 v[2:3], v[2:3], v[234:235] op_sel_hi:[1,0]
	s_waitcnt vmcnt(0)
	v_pk_fma_f32 v[6:7], v[228:229], v[6:7], v[130:131]
	v_pk_fma_f32 v[4:5], v[226:227], v[4:5], v[128:129]
	v_pk_fma_f32 v[2:3], v[232:233], v[2:3], v[134:135]
	v_pk_fma_f32 v[0:1], v[230:231], v[0:1], v[132:133]
	v_mul_f32_e32 v164, v59, v59
	v_fmac_f32_e32 v164, v58, v58
	v_mul_f32_e32 v160, v113, v113
	v_mul_f32_e32 v161, v115, v115
	v_fmac_f32_e32 v160, v112, v112
	v_fmac_f32_e32 v161, v114, v114
	v_add_f32_e32 v160, v160, v161
	v_mul_f32_e32 v162, v117, v117
	v_mul_f32_e32 v163, v119, v119
	v_fmac_f32_e32 v162, v116, v116
	v_fmac_f32_e32 v163, v118, v118
	v_add_f32_e32 v161, v162, v163
	v_add_f32_e32 v160, v160, v161
	v_mul_f32_e32 v161, v61, v61
	v_mul_f32_e32 v162, v63, v63
	v_fmac_f32_e32 v161, v60, v60
	v_fmac_f32_e32 v162, v62, v62
	v_mul_f32_e32 v163, v57, v57
	v_add_f32_e32 v161, v161, v162
	v_fmac_f32_e32 v163, v56, v56
	v_add_f32_e32 v161, v160, v161
	v_add_f32_e32 v162, v163, v164
	v_add_f32_e32 v161, v162, v161
	v_mov_b32_e32 v162, v161
	s_nop 1
	v_permlane16_swap_b32_e32 v161, v162
	v_add_u32_e32 v144, s27, v210
	v_ashrrev_i32_e32 v145, 31, v144
	v_add_u32_e32 v150, 16, v144
	v_ashrrev_i32_e32 v151, 31, v150
	v_add_u32_e32 v148, 32, v144
	v_ashrrev_i32_e32 v149, 31, v148
	v_add_u32_e32 v146, 48, v144
	v_ashrrev_i32_e32 v147, 31, v146
	v_add_u32_e32 v142, 0x80, v144
	v_ashrrev_i32_e32 v143, 31, v142
	v_add_u32_e32 v140, 0x90, v144
	v_ashrrev_i32_e32 v141, 31, v140
	v_add_u32_e32 v138, 0xa0, v144
	v_ashrrev_i32_e32 v139, 31, v138
	v_add_u32_e32 v136, 0xb0, v144
	v_ashrrev_i32_e32 v137, 31, v136
	v_lshl_add_u64 v[218:219], v[200:201], 2, s[22:23]
	global_load_dwordx4 v[240:243], v[218:219], off
	global_load_dwordx4 v[244:247], v[218:219], off offset:16
	global_load_dwordx4 v[226:229], v[218:219], off offset:512
	global_load_dwordx4 v[230:233], v[218:219], off offset:528
	v_add_f32_e32 v128, v161, v162
	v_mov_b32_e32 v129, v128
	s_nop 1
	v_permlane32_swap_b32_e32 v128, v129
	s_and_saveexec_b64 s[16:17], s[8:9]
	s_lshl_b32 s20, s15, 10
	s_add_i32 s20, s25, s20
	v_lshl_add_u32 v130, v208, 4, s20
	v_add_f32_e32 v128, v128, v129
	ds_write_b32 v130, v128
	s_or_b64 exec, exec, s[16:17]
	v_mul_f32_e32 v128, v121, v121
	v_mul_f32_e32 v129, v123, v123
	v_fmac_f32_e32 v128, v120, v120
	v_fmac_f32_e32 v129, v122, v122
	v_add_f32_e32 v128, v128, v129
	v_mul_f32_e32 v129, v125, v125
	v_mul_f32_e32 v130, v127, v127
	v_fmac_f32_e32 v129, v124, v124
	v_fmac_f32_e32 v130, v126, v126
	v_add_f32_e32 v129, v129, v130
	v_add_f32_e32 v128, v128, v129
	v_mul_f32_e32 v129, v53, v53
	v_mul_f32_e32 v130, v55, v55
	v_fmac_f32_e32 v129, v52, v52
	v_fmac_f32_e32 v130, v54, v54
	v_add_f32_e32 v129, v129, v130
	v_add_f32_e32 v128, v128, v129
	v_mul_f32_e32 v129, v49, v49
	v_mul_f32_e32 v130, v51, v51
	v_fmac_f32_e32 v129, v48, v48
	v_fmac_f32_e32 v130, v50, v50
	v_add_f32_e32 v129, v129, v130
	v_add_f32_e32 v128, v129, v128
	v_mov_b32_e32 v129, v128
	s_nop 1
	v_permlane16_swap_b32_e32 v128, v129
	v_add_f32_e32 v128, v128, v129
	v_mov_b32_e32 v129, v128
	s_nop 1
	v_permlane32_swap_b32_e32 v128, v129
	s_and_saveexec_b64 s[16:17], s[8:9]
	s_lshl_b32 s20, s15, 10
	s_add_i32 s20, s25, s20
	v_lshl_add_u32 v130, v208, 4, s20
	v_add_f32_e32 v128, v128, v129
	ds_write_b32 v130, v128 offset:256
	s_or_b64 exec, exec, s[16:17]
	v_mul_f32_e32 v128, v105, v105
	v_mul_f32_e32 v129, v107, v107
	v_fmac_f32_e32 v128, v104, v104
	v_fmac_f32_e32 v129, v106, v106
	v_add_f32_e32 v128, v128, v129
	v_mul_f32_e32 v129, v109, v109
	v_mul_f32_e32 v130, v111, v111
	v_fmac_f32_e32 v129, v108, v108
	v_fmac_f32_e32 v130, v110, v110
	v_add_f32_e32 v129, v129, v130
	v_add_f32_e32 v128, v128, v129
	v_mul_f32_e32 v129, v45, v45
	v_mul_f32_e32 v130, v47, v47
	v_fmac_f32_e32 v129, v44, v44
	v_fmac_f32_e32 v130, v46, v46
	v_add_f32_e32 v129, v129, v130
	v_add_f32_e32 v128, v128, v129
	v_mul_f32_e32 v129, v41, v41
	v_mul_f32_e32 v130, v43, v43
	v_fmac_f32_e32 v129, v40, v40
	v_fmac_f32_e32 v130, v42, v42
	v_add_f32_e32 v129, v129, v130
	v_add_f32_e32 v128, v129, v128
	v_mov_b32_e32 v129, v128
	s_nop 1
	v_permlane16_swap_b32_e32 v128, v129
	v_add_f32_e32 v128, v128, v129
	v_mov_b32_e32 v129, v128
	s_nop 1
	v_permlane32_swap_b32_e32 v128, v129
	s_and_saveexec_b64 s[16:17], s[8:9]
	s_lshl_b32 s20, s15, 10
	s_add_i32 s20, s25, s20
	v_lshl_add_u32 v130, v208, 4, s20
	v_add_f32_e32 v128, v128, v129
	ds_write_b32 v130, v128 offset:512
	s_or_b64 exec, exec, s[16:17]
	v_mul_f32_e32 v128, v101, v101
	v_mul_f32_e32 v129, v103, v103
	v_fmac_f32_e32 v128, v100, v100
	v_fmac_f32_e32 v129, v102, v102
	v_add_f32_e32 v128, v128, v129
	v_mul_f32_e32 v129, v97, v97
	v_mul_f32_e32 v130, v99, v99
	v_fmac_f32_e32 v129, v96, v96
	v_fmac_f32_e32 v130, v98, v98
	v_add_f32_e32 v129, v129, v130
	v_add_f32_e32 v128, v128, v129
	v_mul_f32_e32 v129, v37, v37
	v_mul_f32_e32 v130, v39, v39
	v_fmac_f32_e32 v129, v36, v36
	v_fmac_f32_e32 v130, v38, v38
	v_add_f32_e32 v129, v129, v130
	v_add_f32_e32 v128, v128, v129
	v_mul_f32_e32 v129, v33, v33
	v_mul_f32_e32 v130, v35, v35
	v_fmac_f32_e32 v129, v32, v32
	v_fmac_f32_e32 v130, v34, v34
	v_add_f32_e32 v129, v129, v130
	v_add_f32_e32 v128, v129, v128
	v_mov_b32_e32 v129, v128
	s_nop 1
	v_permlane16_swap_b32_e32 v128, v129
	v_add_f32_e32 v128, v128, v129
	v_mov_b32_e32 v129, v128
	s_nop 1
	v_permlane32_swap_b32_e32 v128, v129
	s_and_saveexec_b64 s[16:17], s[8:9]
	s_lshl_b32 s20, s15, 10
	s_add_i32 s20, s25, s20
	v_lshl_add_u32 v130, v208, 4, s20
	v_add_f32_e32 v128, v128, v129
	ds_write_b32 v130, v128 offset:768
	s_or_b64 exec, exec, s[16:17]
	v_mul_f32_e32 v128, v93, v93
	v_mul_f32_e32 v129, v95, v95
	v_fmac_f32_e32 v128, v92, v92
	v_fmac_f32_e32 v129, v94, v94
	v_add_f32_e32 v128, v128, v129
	v_mul_f32_e32 v129, v89, v89
	v_mul_f32_e32 v130, v91, v91
	v_fmac_f32_e32 v129, v88, v88
	v_fmac_f32_e32 v130, v90, v90
	v_add_f32_e32 v129, v129, v130
	v_add_f32_e32 v128, v128, v129
	v_mul_f32_e32 v129, v29, v29
	v_mul_f32_e32 v130, v31, v31
	v_fmac_f32_e32 v129, v28, v28
	v_fmac_f32_e32 v130, v30, v30
	v_add_f32_e32 v129, v129, v130
	v_add_f32_e32 v128, v128, v129
	v_mul_f32_e32 v129, v25, v25
	v_mul_f32_e32 v130, v27, v27
	v_fmac_f32_e32 v129, v24, v24
	v_fmac_f32_e32 v130, v26, v26
	v_add_f32_e32 v129, v129, v130
	v_add_f32_e32 v128, v129, v128
	v_mov_b32_e32 v129, v128
	s_nop 1
	v_permlane16_swap_b32_e32 v128, v129
	v_add_f32_e32 v128, v128, v129
	v_mov_b32_e32 v129, v128
	s_nop 1
	v_permlane32_swap_b32_e32 v128, v129
	s_and_saveexec_b64 s[16:17], s[8:9]
	s_lshl_b32 s20, s15, 10
	s_add_i32 s20, s25, s20
	v_lshl_add_u32 v130, v208, 4, s20
	v_add_f32_e32 v128, v128, v129
	ds_write_b32 v130, v128 offset:2048
	s_or_b64 exec, exec, s[16:17]
	v_mul_f32_e32 v128, v85, v85
	v_mul_f32_e32 v129, v87, v87
	v_fmac_f32_e32 v128, v84, v84
	v_fmac_f32_e32 v129, v86, v86
	v_add_f32_e32 v128, v128, v129
	v_mul_f32_e32 v129, v81, v81
	v_mul_f32_e32 v130, v83, v83
	v_fmac_f32_e32 v129, v80, v80
	v_fmac_f32_e32 v130, v82, v82
	v_add_f32_e32 v129, v129, v130
	v_add_f32_e32 v128, v128, v129
	v_mul_f32_e32 v129, v21, v21
	v_mul_f32_e32 v130, v23, v23
	v_fmac_f32_e32 v129, v20, v20
	v_fmac_f32_e32 v130, v22, v22
	v_add_f32_e32 v129, v129, v130
	v_add_f32_e32 v128, v128, v129
	v_mul_f32_e32 v129, v17, v17
	v_mul_f32_e32 v130, v19, v19
	v_fmac_f32_e32 v129, v16, v16
	v_fmac_f32_e32 v130, v18, v18
	v_add_f32_e32 v129, v129, v130
	v_add_f32_e32 v128, v129, v128
	v_mov_b32_e32 v129, v128
	s_nop 1
	v_permlane16_swap_b32_e32 v128, v129
	v_add_f32_e32 v128, v128, v129
	v_mov_b32_e32 v129, v128
	s_nop 1
	v_permlane32_swap_b32_e32 v128, v129
	s_and_saveexec_b64 s[16:17], s[8:9]
	s_lshl_b32 s20, s15, 10
	s_add_i32 s20, s25, s20
	v_lshl_add_u32 v130, v208, 4, s20
	v_add_f32_e32 v128, v128, v129
	ds_write_b32 v130, v128 offset:2304
	s_or_b64 exec, exec, s[16:17]
	v_mul_f32_e32 v128, v77, v77
	v_mul_f32_e32 v129, v79, v79
	v_fmac_f32_e32 v128, v76, v76
	v_fmac_f32_e32 v129, v78, v78
	v_add_f32_e32 v128, v128, v129
	v_mul_f32_e32 v129, v73, v73
	v_mul_f32_e32 v130, v75, v75
	v_fmac_f32_e32 v129, v72, v72
	v_fmac_f32_e32 v130, v74, v74
	v_add_f32_e32 v129, v129, v130
	v_add_f32_e32 v128, v128, v129
	v_mul_f32_e32 v129, v13, v13
	v_mul_f32_e32 v130, v15, v15
	v_fmac_f32_e32 v129, v12, v12
	v_fmac_f32_e32 v130, v14, v14
	v_add_f32_e32 v129, v129, v130
	v_add_f32_e32 v128, v128, v129
	v_mul_f32_e32 v129, v9, v9
	v_mul_f32_e32 v130, v11, v11
	v_fmac_f32_e32 v129, v8, v8
	v_fmac_f32_e32 v130, v10, v10
	v_add_f32_e32 v129, v129, v130
	v_add_f32_e32 v128, v129, v128
	v_mov_b32_e32 v129, v128
	s_nop 1
	v_permlane16_swap_b32_e32 v128, v129
	v_add_f32_e32 v128, v128, v129
	v_mov_b32_e32 v129, v128
	s_nop 1
	v_permlane32_swap_b32_e32 v128, v129
	s_and_saveexec_b64 s[16:17], s[8:9]
	s_lshl_b32 s20, s15, 10
	s_add_i32 s20, s25, s20
	v_lshl_add_u32 v130, v208, 4, s20
	v_add_f32_e32 v128, v128, v129
	ds_write_b32 v130, v128 offset:2560
	s_or_b64 exec, exec, s[16:17]
	v_mul_f32_e32 v128, v69, v69
	v_mul_f32_e32 v129, v71, v71
	v_fmac_f32_e32 v128, v68, v68
	v_fmac_f32_e32 v129, v70, v70
	v_add_f32_e32 v128, v128, v129
	v_mul_f32_e32 v129, v65, v65
	v_mul_f32_e32 v130, v67, v67
	v_fmac_f32_e32 v129, v64, v64
	v_fmac_f32_e32 v130, v66, v66
	v_add_f32_e32 v129, v129, v130
	v_add_f32_e32 v128, v128, v129
	v_mul_f32_e32 v129, v5, v5
	v_mul_f32_e32 v130, v7, v7
	v_fmac_f32_e32 v129, v4, v4
	v_fmac_f32_e32 v130, v6, v6
	v_add_f32_e32 v129, v129, v130
	v_add_f32_e32 v128, v128, v129
	v_mul_f32_e32 v129, v1, v1
	v_mul_f32_e32 v130, v3, v3
	v_fmac_f32_e32 v129, v0, v0
	v_fmac_f32_e32 v130, v2, v2
	v_add_f32_e32 v129, v129, v130
	v_add_f32_e32 v128, v129, v128
	v_mov_b32_e32 v129, v128
	s_nop 1
	v_permlane16_swap_b32_e32 v128, v129
	v_add_f32_e32 v128, v128, v129
	v_mov_b32_e32 v129, v128
	s_nop 1
	v_permlane32_swap_b32_e32 v128, v129
	s_and_saveexec_b64 s[16:17], s[8:9]
	s_lshl_b32 s8, s15, 10
	s_add_i32 s25, s25, s8
	v_lshl_add_u32 v130, v208, 4, s25
	v_add_f32_e32 v128, v128, v129
	ds_write_b32 v130, v128 offset:2816
	s_or_b64 exec, exec, s[16:17]
	s_waitcnt lgkmcnt(0)
	s_barrier
	s_add_u32 s8, s18, 0x29b80000
	s_addc_u32 s9, s19, 0
	s_and_saveexec_b64 s[16:17], s[10:11]
	s_cbranch_execz .LBB0_737
	ds_read_b128 v[128:131], v212
	v_lshlrev_b64 v[132:133], 5, v[202:203]
	s_ashr_i32 s47, s46, 31
	s_waitcnt lgkmcnt(0)
	v_mov_b32_e32 v134, v129
	v_mov_b32_e32 v135, v130
	v_mov_b32_e32 v129, v131
	v_pk_add_f32 v[128:129], v[134:135], v[128:129]
	v_lshl_add_u64 v[130:131], s[8:9], 0, v[132:133]
	v_pk_add_f32 v[128:129], v[128:129], v[128:129] op_sel:[0,1] op_sel_hi:[1,0]
	v_lshl_add_u64 v[130:131], s[46:47], 3, v[130:131]
	v_mov_b32_e32 v129, 0
	global_store_dwordx2 v[130:131], v[128:129], off sc1

.LBB0_754:
	s_or_b64 exec, exec, s[12:13]
	v_mov_b32_e32 v128, s22
	v_mov_b32_e32 v129, s23
	s_waitcnt lgkmcnt(0)
	s_barrier
	v_lshl_add_u64 v[152:153], v[200:201], 2, v[128:129]
	ds_read_b32 v158, v209 offset:8192
	v_lshlrev_b64 v[144:145], 10, v[144:145]
	s_add_u32 s8, s18, 0x29d00000
	v_lshl_add_u64 v[160:161], v[144:145], 0, v[200:201]
	s_addc_u32 s9, s19, 0
	v_cvt_pk_bf16_f32 v154, v112, v113
	v_cvt_pk_bf16_f32 v155, v114, v115
	v_cvt_pk_bf16_f32 v156, v116, v117
	v_lshlrev_b64 v[160:161], 1, v[160:161]
	s_waitcnt lgkmcnt(0)
	v_pk_mul_f32 v[114:115], v[114:115], v[158:159] op_sel_hi:[1,0]
	v_pk_mul_f32 v[112:113], v[112:113], v[158:159] op_sel_hi:[1,0]
	v_pk_mul_f32 v[116:117], v[116:117], v[158:159] op_sel_hi:[1,0]
	v_cvt_pk_bf16_f32 v157, v118, v119
	v_lshl_add_u64 v[168:169], s[8:9], 0, v[160:161]
	v_pk_mul_f32 v[118:119], v[118:119], v[158:159] op_sel_hi:[1,0]
	global_store_dwordx4 v[168:169], v[154:157], off nt
	v_lshlrev_b64 v[150:151], 10, v[150:151]
	s_add_u32 s10, s18, 0x12300000
	v_lshl_add_u64 v[162:163], v[150:151], 0, v[200:201]
	s_addc_u32 s11, s19, 0
	v_lshlrev_b64 v[162:163], 1, v[162:163]
	v_lshl_add_u64 v[154:155], s[10:11], 0, v[160:161]
	v_lshl_add_u64 v[170:171], s[8:9], 0, v[162:163]
	v_lshlrev_b64 v[148:149], 10, v[148:149]
	v_lshl_add_u64 v[164:165], v[148:149], 0, v[200:201]
	v_lshl_add_u64 v[156:157], s[10:11], 0, v[162:163]
	v_lshlrev_b64 v[164:165], 1, v[164:165]
	v_lshl_add_u64 v[172:173], s[8:9], 0, v[164:165]
	v_lshlrev_b64 v[146:147], 10, v[146:147]
	v_lshl_add_u64 v[166:167], v[146:147], 0, v[200:201]
	v_lshlrev_b64 v[166:167], 1, v[166:167]
	v_lshl_add_u64 v[160:161], s[10:11], 0, v[164:165]
	v_lshl_add_u64 v[174:175], s[8:9], 0, v[166:167]
	v_pk_mul_f32 v[114:115], v[242:243], v[114:115]
	v_pk_mul_f32 v[112:113], v[240:241], v[112:113]
	v_pk_mul_f32 v[116:117], v[244:245], v[116:117]
	v_pk_mul_f32 v[118:119], v[246:247], v[118:119]
	v_cvt_pk_bf16_f32 v112, v112, v113
	v_cvt_pk_bf16_f32 v113, v114, v115
	v_cvt_pk_bf16_f32 v114, v116, v117
	s_nop 0
	v_cvt_pk_bf16_f32 v115, v118, v119
	ds_read_b32 v116, v209 offset:8256
	global_store_dwordx4 v[154:155], v[112:115], off
	s_waitcnt lgkmcnt(0)
	v_pk_mul_f32 v[118:119], v[126:127], v[116:117] op_sel_hi:[1,0]
	v_cvt_pk_bf16_f32 v112, v120, v121
	v_cvt_pk_bf16_f32 v113, v122, v123
	v_cvt_pk_bf16_f32 v114, v124, v125
	v_cvt_pk_bf16_f32 v115, v126, v127
	global_store_dwordx4 v[170:171], v[112:115], off nt
	v_pk_mul_f32 v[118:119], v[246:247], v[118:119]
	s_nop 0
	v_pk_mul_f32 v[112:113], v[122:123], v[116:117] op_sel_hi:[1,0]
	v_pk_mul_f32 v[114:115], v[120:121], v[116:117] op_sel_hi:[1,0]
	v_pk_mul_f32 v[116:117], v[124:125], v[116:117] op_sel_hi:[1,0]
	v_pk_mul_f32 v[120:121], v[242:243], v[112:113]
	v_pk_mul_f32 v[112:113], v[240:241], v[114:115]
	v_pk_mul_f32 v[114:115], v[244:245], v[116:117]
	v_cvt_pk_bf16_f32 v112, v112, v113
	v_cvt_pk_bf16_f32 v113, v120, v121
	s_nop 0
	v_cvt_pk_bf16_f32 v114, v114, v115
	v_cvt_pk_bf16_f32 v115, v118, v119
	ds_read_b32 v116, v209 offset:8320
	global_store_dwordx4 v[156:157], v[112:115], off
	s_nop 1
	v_cvt_pk_bf16_f32 v112, v104, v105
	v_cvt_pk_bf16_f32 v113, v106, v107
	v_cvt_pk_bf16_f32 v114, v108, v109
	s_waitcnt lgkmcnt(0)
	v_pk_mul_f32 v[106:107], v[106:107], v[116:117] op_sel_hi:[1,0]
	v_pk_mul_f32 v[104:105], v[104:105], v[116:117] op_sel_hi:[1,0]
	v_pk_mul_f32 v[108:109], v[108:109], v[116:117] op_sel_hi:[1,0]
	v_cvt_pk_bf16_f32 v115, v110, v111
	v_pk_mul_f32 v[110:111], v[110:111], v[116:117] op_sel_hi:[1,0]
	v_pk_mul_f32 v[106:107], v[242:243], v[106:107]
	v_pk_mul_f32 v[104:105], v[240:241], v[104:105]
	v_pk_mul_f32 v[108:109], v[244:245], v[108:109]
	global_store_dwordx4 v[172:173], v[112:115], off nt
	v_pk_mul_f32 v[110:111], v[246:247], v[110:111]
	v_cvt_pk_bf16_f32 v104, v104, v105
	v_cvt_pk_bf16_f32 v105, v106, v107
	v_cvt_pk_bf16_f32 v106, v108, v109
	s_nop 0
	v_cvt_pk_bf16_f32 v107, v110, v111
	ds_read_b32 v108, v209 offset:8384
	global_store_dwordx4 v[160:161], v[104:107], off
	s_nop 1
	v_cvt_pk_bf16_f32 v104, v100, v101
	v_cvt_pk_bf16_f32 v105, v102, v103
	v_cvt_pk_bf16_f32 v106, v96, v97
	v_cvt_pk_bf16_f32 v107, v98, v99
	s_waitcnt lgkmcnt(0)
	v_pk_mul_f32 v[102:103], v[102:103], v[108:109] op_sel_hi:[1,0]
	v_pk_mul_f32 v[98:99], v[98:99], v[108:109] op_sel_hi:[1,0]
	v_pk_mul_f32 v[96:97], v[96:97], v[108:109] op_sel_hi:[1,0]
	global_store_dwordx4 v[174:175], v[104:107], off nt
	v_pk_mul_f32 v[100:101], v[100:101], v[108:109] op_sel_hi:[1,0]
	v_pk_mul_f32 v[102:103], v[242:243], v[102:103]
	v_pk_mul_f32 v[104:105], v[246:247], v[98:99]
	v_pk_mul_f32 v[98:99], v[244:245], v[96:97]
	v_pk_mul_f32 v[100:101], v[240:241], v[100:101]
	s_nop 0
	v_cvt_pk_bf16_f32 v96, v100, v101
	v_cvt_pk_bf16_f32 v97, v102, v103
	v_cvt_pk_bf16_f32 v98, v98, v99
	v_cvt_pk_bf16_f32 v99, v104, v105
	ds_read_b32 v102, v209 offset:8704
	v_lshl_add_u64 v[100:101], s[10:11], 0, v[166:167]
	global_store_dwordx4 v[100:101], v[96:99], off
	s_nop 1
	v_lshlrev_b64 v[96:97], 10, v[142:143]
	v_lshl_add_u64 v[104:105], v[96:97], 0, v[200:201]
	v_lshlrev_b64 v[104:105], 1, v[104:105]
	v_cvt_pk_bf16_f32 v98, v92, v93
	v_cvt_pk_bf16_f32 v99, v94, v95
	v_cvt_pk_bf16_f32 v100, v88, v89
	v_cvt_pk_bf16_f32 v101, v90, v91
	v_lshl_add_u64 v[106:107], s[8:9], 0, v[104:105]
	s_waitcnt lgkmcnt(0)
	v_pk_mul_f32 v[94:95], v[94:95], v[102:103] op_sel_hi:[1,0]
	v_pk_mul_f32 v[90:91], v[90:91], v[102:103] op_sel_hi:[1,0]
	v_pk_mul_f32 v[88:89], v[88:89], v[102:103] op_sel_hi:[1,0]
	global_store_dwordx4 v[106:107], v[98:101], off nt
	v_pk_mul_f32 v[92:93], v[92:93], v[102:103] op_sel_hi:[1,0]
	v_pk_mul_f32 v[94:95], v[242:243], v[94:95]
	v_pk_mul_f32 v[98:99], v[246:247], v[90:91]
	v_pk_mul_f32 v[90:91], v[244:245], v[88:89]
	v_pk_mul_f32 v[92:93], v[240:241], v[92:93]
	s_nop 0
	v_cvt_pk_bf16_f32 v88, v92, v93
	v_cvt_pk_bf16_f32 v89, v94, v95
	v_cvt_pk_bf16_f32 v90, v90, v91
	v_cvt_pk_bf16_f32 v91, v98, v99
	ds_read_b32 v94, v209 offset:8768
	v_lshl_add_u64 v[92:93], s[10:11], 0, v[104:105]
	global_store_dwordx4 v[92:93], v[88:91], off
	s_nop 1
	v_lshlrev_b64 v[88:89], 10, v[140:141]
	v_lshl_add_u64 v[98:99], v[88:89], 0, v[200:201]
	v_lshlrev_b64 v[98:99], 1, v[98:99]
	v_cvt_pk_bf16_f32 v90, v84, v85
	v_cvt_pk_bf16_f32 v91, v86, v87
	v_cvt_pk_bf16_f32 v92, v80, v81
	v_cvt_pk_bf16_f32 v93, v82, v83
	v_lshl_add_u64 v[100:101], s[8:9], 0, v[98:99]
	s_waitcnt lgkmcnt(0)
	v_pk_mul_f32 v[86:87], v[86:87], v[94:95] op_sel_hi:[1,0]
	v_pk_mul_f32 v[82:83], v[82:83], v[94:95] op_sel_hi:[1,0]
	v_pk_mul_f32 v[80:81], v[80:81], v[94:95] op_sel_hi:[1,0]
	global_store_dwordx4 v[100:101], v[90:93], off nt
	v_pk_mul_f32 v[84:85], v[84:85], v[94:95] op_sel_hi:[1,0]
	v_pk_mul_f32 v[86:87], v[242:243], v[86:87]
	v_pk_mul_f32 v[90:91], v[246:247], v[82:83]
	v_pk_mul_f32 v[82:83], v[244:245], v[80:81]
	v_pk_mul_f32 v[84:85], v[240:241], v[84:85]
	s_nop 0
	v_cvt_pk_bf16_f32 v80, v84, v85
	v_cvt_pk_bf16_f32 v81, v86, v87
	v_cvt_pk_bf16_f32 v82, v82, v83
	v_cvt_pk_bf16_f32 v83, v90, v91
	ds_read_b32 v86, v209 offset:8832
	v_lshl_add_u64 v[84:85], s[10:11], 0, v[98:99]
	global_store_dwordx4 v[84:85], v[80:83], off
	s_nop 1
	v_lshlrev_b64 v[80:81], 10, v[138:139]
	v_lshl_add_u64 v[90:91], v[80:81], 0, v[200:201]
	v_lshlrev_b64 v[90:91], 1, v[90:91]
	v_cvt_pk_bf16_f32 v82, v76, v77
	v_cvt_pk_bf16_f32 v83, v78, v79
	v_cvt_pk_bf16_f32 v84, v72, v73
	v_cvt_pk_bf16_f32 v85, v74, v75
	v_lshl_add_u64 v[92:93], s[8:9], 0, v[90:91]
	s_waitcnt lgkmcnt(0)
	v_pk_mul_f32 v[78:79], v[78:79], v[86:87] op_sel_hi:[1,0]
	v_pk_mul_f32 v[74:75], v[74:75], v[86:87] op_sel_hi:[1,0]
	v_pk_mul_f32 v[72:73], v[72:73], v[86:87] op_sel_hi:[1,0]
	global_store_dwordx4 v[92:93], v[82:85], off nt
	v_pk_mul_f32 v[76:77], v[76:77], v[86:87] op_sel_hi:[1,0]
	v_pk_mul_f32 v[78:79], v[242:243], v[78:79]
	v_pk_mul_f32 v[82:83], v[246:247], v[74:75]
	v_pk_mul_f32 v[74:75], v[244:245], v[72:73]
	v_pk_mul_f32 v[76:77], v[240:241], v[76:77]
	s_nop 0
	v_cvt_pk_bf16_f32 v72, v76, v77
	v_cvt_pk_bf16_f32 v73, v78, v79
	v_cvt_pk_bf16_f32 v74, v74, v75
	v_cvt_pk_bf16_f32 v75, v82, v83
	ds_read_b32 v78, v209 offset:8896
	v_lshl_add_u64 v[76:77], s[10:11], 0, v[90:91]
	global_store_dwordx4 v[76:77], v[72:75], off
	s_nop 1
	v_lshlrev_b64 v[72:73], 10, v[136:137]
	v_lshl_add_u64 v[82:83], v[72:73], 0, v[200:201]
	v_cvt_pk_bf16_f32 v74, v68, v69
	v_lshlrev_b64 v[82:83], 1, v[82:83]
	s_waitcnt lgkmcnt(0)
	v_pk_mul_f32 v[68:69], v[68:69], v[78:79] op_sel_hi:[1,0]
	v_cvt_pk_bf16_f32 v75, v70, v71
	v_cvt_pk_bf16_f32 v76, v64, v65
	v_cvt_pk_bf16_f32 v77, v66, v67
	v_lshl_add_u64 v[84:85], s[8:9], 0, v[82:83]
	v_pk_mul_f32 v[68:69], v[240:241], v[68:69]
	v_pk_mul_f32 v[66:67], v[66:67], v[78:79] op_sel_hi:[1,0]
	v_pk_mul_f32 v[64:65], v[64:65], v[78:79] op_sel_hi:[1,0]
	global_store_dwordx4 v[84:85], v[74:77], off nt
	v_pk_mul_f32 v[70:71], v[70:71], v[78:79] op_sel_hi:[1,0]
	v_or_b32_e32 v200, 0x80, v200
	v_pk_mul_f32 v[74:75], v[246:247], v[66:67]
	v_pk_mul_f32 v[66:67], v[244:245], v[64:65]
	v_cvt_pk_bf16_f32 v64, v68, v69
	v_lshl_add_u64 v[68:69], s[10:11], 0, v[82:83]
	v_pk_mul_f32 v[70:71], v[242:243], v[70:71]
	v_lshl_add_u64 v[82:83], v[144:145], 0, v[200:201]
	v_cvt_pk_bf16_f32 v65, v70, v71
	v_cvt_pk_bf16_f32 v66, v66, v67
	v_cvt_pk_bf16_f32 v67, v74, v75
	global_store_dwordx4 v[68:69], v[64:67], off
	s_nop 0
	ds_read_b32 v78, v209 offset:8192
	v_cvt_pk_bf16_f32 v74, v60, v61
	v_lshlrev_b64 v[82:83], 1, v[82:83]
	v_cvt_pk_bf16_f32 v75, v62, v63
	v_cvt_pk_bf16_f32 v76, v56, v57
	s_waitcnt lgkmcnt(0)
	v_pk_mul_f32 v[60:61], v[60:61], v[78:79] op_sel_hi:[1,0]
	v_cvt_pk_bf16_f32 v77, v58, v59
	v_lshl_add_u64 v[84:85], s[8:9], 0, v[82:83]
	v_pk_mul_f32 v[58:59], v[58:59], v[78:79] op_sel_hi:[1,0]
	v_pk_mul_f32 v[56:57], v[56:57], v[78:79] op_sel_hi:[1,0]
	global_store_dwordx4 v[84:85], v[74:77], off nt
	v_pk_mul_f32 v[62:63], v[62:63], v[78:79] op_sel_hi:[1,0]
	v_pk_mul_f32 v[60:61], v[226:227], v[60:61]
	v_pk_mul_f32 v[74:75], v[232:233], v[58:59]
	v_pk_mul_f32 v[58:59], v[230:231], v[56:57]
	v_cvt_pk_bf16_f32 v56, v60, v61
	v_lshl_add_u64 v[60:61], s[10:11], 0, v[82:83]
	v_pk_mul_f32 v[62:63], v[228:229], v[62:63]
	s_nop 0
	v_cvt_pk_bf16_f32 v57, v62, v63
	v_cvt_pk_bf16_f32 v58, v58, v59
	v_cvt_pk_bf16_f32 v59, v74, v75
	global_store_dwordx4 v[60:61], v[56:59], off
	ds_read_b32 v60, v209 offset:8256
	v_lshl_add_u64 v[62:63], v[150:151], 0, v[200:201]
	v_cvt_pk_bf16_f32 v56, v52, v53
	v_lshlrev_b64 v[62:63], 1, v[62:63]
	v_cvt_pk_bf16_f32 v57, v54, v55
	s_waitcnt lgkmcnt(0)
	v_pk_mul_f32 v[52:53], v[52:53], v[60:61] op_sel_hi:[1,0]
	v_cvt_pk_bf16_f32 v58, v48, v49
	v_cvt_pk_bf16_f32 v59, v50, v51
	v_lshl_add_u64 v[74:75], s[8:9], 0, v[62:63]
	v_pk_mul_f32 v[52:53], v[226:227], v[52:53]
	v_pk_mul_f32 v[50:51], v[50:51], v[60:61] op_sel_hi:[1,0]
	v_pk_mul_f32 v[48:49], v[48:49], v[60:61] op_sel_hi:[1,0]
	global_store_dwordx4 v[74:75], v[56:59], off nt
	v_pk_mul_f32 v[54:55], v[54:55], v[60:61] op_sel_hi:[1,0]
	s_nop 0
	v_pk_mul_f32 v[56:57], v[232:233], v[50:51]
	v_pk_mul_f32 v[50:51], v[230:231], v[48:49]
	v_cvt_pk_bf16_f32 v48, v52, v53
	v_lshl_add_u64 v[52:53], s[10:11], 0, v[62:63]
	v_pk_mul_f32 v[54:55], v[228:229], v[54:55]
	s_nop 0
	v_cvt_pk_bf16_f32 v49, v54, v55
	v_cvt_pk_bf16_f32 v50, v50, v51
	v_cvt_pk_bf16_f32 v51, v56, v57
	global_store_dwordx4 v[52:53], v[48:51], off
	ds_read_b32 v52, v209 offset:8320
	v_lshl_add_u64 v[54:55], v[148:149], 0, v[200:201]
	v_cvt_pk_bf16_f32 v48, v44, v45
	v_lshlrev_b64 v[54:55], 1, v[54:55]
	v_cvt_pk_bf16_f32 v49, v46, v47
	s_waitcnt lgkmcnt(0)
	v_pk_mul_f32 v[44:45], v[44:45], v[52:53] op_sel_hi:[1,0]
	v_cvt_pk_bf16_f32 v50, v40, v41
	v_cvt_pk_bf16_f32 v51, v42, v43
	v_lshl_add_u64 v[56:57], s[8:9], 0, v[54:55]
	v_pk_mul_f32 v[44:45], v[226:227], v[44:45]
	v_pk_mul_f32 v[42:43], v[42:43], v[52:53] op_sel_hi:[1,0]
	v_pk_mul_f32 v[40:41], v[40:41], v[52:53] op_sel_hi:[1,0]
	global_store_dwordx4 v[56:57], v[48:51], off nt
	v_pk_mul_f32 v[46:47], v[46:47], v[52:53] op_sel_hi:[1,0]
	s_nop 0
	v_pk_mul_f32 v[48:49], v[232:233], v[42:43]
	v_pk_mul_f32 v[42:43], v[230:231], v[40:41]
	v_cvt_pk_bf16_f32 v40, v44, v45
	v_lshl_add_u64 v[44:45], s[10:11], 0, v[54:55]
	v_pk_mul_f32 v[46:47], v[228:229], v[46:47]
	s_nop 0
	v_cvt_pk_bf16_f32 v41, v46, v47
	v_cvt_pk_bf16_f32 v42, v42, v43
	v_cvt_pk_bf16_f32 v43, v48, v49
	global_store_dwordx4 v[44:45], v[40:43], off
	ds_read_b32 v44, v209 offset:8384
	v_lshl_add_u64 v[46:47], v[146:147], 0, v[200:201]
	v_cvt_pk_bf16_f32 v40, v36, v37
	v_lshlrev_b64 v[46:47], 1, v[46:47]
	v_cvt_pk_bf16_f32 v41, v38, v39
	s_waitcnt lgkmcnt(0)
	v_pk_mul_f32 v[36:37], v[36:37], v[44:45] op_sel_hi:[1,0]
	v_cvt_pk_bf16_f32 v42, v32, v33
	v_cvt_pk_bf16_f32 v43, v34, v35
	v_lshl_add_u64 v[48:49], s[8:9], 0, v[46:47]
	v_pk_mul_f32 v[36:37], v[226:227], v[36:37]
	v_pk_mul_f32 v[34:35], v[34:35], v[44:45] op_sel_hi:[1,0]
	v_pk_mul_f32 v[32:33], v[32:33], v[44:45] op_sel_hi:[1,0]
	global_store_dwordx4 v[48:49], v[40:43], off nt
	v_pk_mul_f32 v[38:39], v[38:39], v[44:45] op_sel_hi:[1,0]
	s_nop 0
	v_pk_mul_f32 v[40:41], v[232:233], v[34:35]
	v_pk_mul_f32 v[34:35], v[230:231], v[32:33]
	v_cvt_pk_bf16_f32 v32, v36, v37
	v_lshl_add_u64 v[36:37], s[10:11], 0, v[46:47]
	v_pk_mul_f32 v[38:39], v[228:229], v[38:39]
	s_nop 0
	v_cvt_pk_bf16_f32 v33, v38, v39
	v_cvt_pk_bf16_f32 v34, v34, v35
	v_cvt_pk_bf16_f32 v35, v40, v41
	global_store_dwordx4 v[36:37], v[32:35], off
	ds_read_b32 v36, v209 offset:8704
	v_lshl_add_u64 v[38:39], v[96:97], 0, v[200:201]
	v_cvt_pk_bf16_f32 v32, v28, v29
	v_lshlrev_b64 v[38:39], 1, v[38:39]
	v_cvt_pk_bf16_f32 v33, v30, v31
	s_waitcnt lgkmcnt(0)
	v_pk_mul_f32 v[28:29], v[28:29], v[36:37] op_sel_hi:[1,0]
	v_cvt_pk_bf16_f32 v34, v24, v25
	v_cvt_pk_bf16_f32 v35, v26, v27
	v_lshl_add_u64 v[40:41], s[8:9], 0, v[38:39]
	v_pk_mul_f32 v[28:29], v[226:227], v[28:29]
	v_pk_mul_f32 v[26:27], v[26:27], v[36:37] op_sel_hi:[1,0]
	v_pk_mul_f32 v[24:25], v[24:25], v[36:37] op_sel_hi:[1,0]
	global_store_dwordx4 v[40:41], v[32:35], off nt
	v_pk_mul_f32 v[30:31], v[30:31], v[36:37] op_sel_hi:[1,0]
	s_nop 0
	v_pk_mul_f32 v[32:33], v[232:233], v[26:27]
	v_pk_mul_f32 v[26:27], v[230:231], v[24:25]
	v_cvt_pk_bf16_f32 v24, v28, v29
	v_lshl_add_u64 v[28:29], s[10:11], 0, v[38:39]
	v_pk_mul_f32 v[30:31], v[228:229], v[30:31]
	s_nop 0
	v_cvt_pk_bf16_f32 v25, v30, v31
	v_cvt_pk_bf16_f32 v26, v26, v27
	v_cvt_pk_bf16_f32 v27, v32, v33
	global_store_dwordx4 v[28:29], v[24:27], off
	ds_read_b32 v28, v209 offset:8768
	v_lshl_add_u64 v[30:31], v[88:89], 0, v[200:201]
	v_cvt_pk_bf16_f32 v24, v20, v21
	v_lshlrev_b64 v[30:31], 1, v[30:31]
	v_cvt_pk_bf16_f32 v25, v22, v23
	s_waitcnt lgkmcnt(0)
	v_pk_mul_f32 v[20:21], v[20:21], v[28:29] op_sel_hi:[1,0]
	v_cvt_pk_bf16_f32 v26, v16, v17
	v_cvt_pk_bf16_f32 v27, v18, v19
	v_lshl_add_u64 v[32:33], s[8:9], 0, v[30:31]
	v_pk_mul_f32 v[20:21], v[226:227], v[20:21]
	v_pk_mul_f32 v[18:19], v[18:19], v[28:29] op_sel_hi:[1,0]
	v_pk_mul_f32 v[16:17], v[16:17], v[28:29] op_sel_hi:[1,0]
	global_store_dwordx4 v[32:33], v[24:27], off nt
	v_pk_mul_f32 v[22:23], v[22:23], v[28:29] op_sel_hi:[1,0]
	s_nop 0
	v_pk_mul_f32 v[24:25], v[232:233], v[18:19]
	v_pk_mul_f32 v[18:19], v[230:231], v[16:17]
	v_cvt_pk_bf16_f32 v16, v20, v21
	v_lshl_add_u64 v[20:21], s[10:11], 0, v[30:31]
	v_pk_mul_f32 v[22:23], v[228:229], v[22:23]
	s_nop 0
	v_cvt_pk_bf16_f32 v17, v22, v23
	v_cvt_pk_bf16_f32 v18, v18, v19
	v_cvt_pk_bf16_f32 v19, v24, v25
	global_store_dwordx4 v[20:21], v[16:19], off
	ds_read_b32 v20, v209 offset:8832
	v_lshl_add_u64 v[22:23], v[80:81], 0, v[200:201]
	v_cvt_pk_bf16_f32 v16, v12, v13
	v_lshlrev_b64 v[22:23], 1, v[22:23]
	v_cvt_pk_bf16_f32 v17, v14, v15
	s_waitcnt lgkmcnt(0)
	v_pk_mul_f32 v[12:13], v[12:13], v[20:21] op_sel_hi:[1,0]
	v_cvt_pk_bf16_f32 v18, v8, v9
	v_cvt_pk_bf16_f32 v19, v10, v11
	v_lshl_add_u64 v[24:25], s[8:9], 0, v[22:23]
	v_pk_mul_f32 v[12:13], v[226:227], v[12:13]
	v_pk_mul_f32 v[10:11], v[10:11], v[20:21] op_sel_hi:[1,0]
	v_pk_mul_f32 v[8:9], v[8:9], v[20:21] op_sel_hi:[1,0]
	global_store_dwordx4 v[24:25], v[16:19], off nt
	v_pk_mul_f32 v[14:15], v[14:15], v[20:21] op_sel_hi:[1,0]
	s_nop 0
	v_pk_mul_f32 v[16:17], v[232:233], v[10:11]
	v_pk_mul_f32 v[10:11], v[230:231], v[8:9]
	v_cvt_pk_bf16_f32 v8, v12, v13
	v_lshl_add_u64 v[12:13], s[10:11], 0, v[22:23]
	v_pk_mul_f32 v[14:15], v[228:229], v[14:15]
	s_nop 0
	v_cvt_pk_bf16_f32 v9, v14, v15
	v_cvt_pk_bf16_f32 v10, v10, v11
	v_cvt_pk_bf16_f32 v11, v16, v17
	global_store_dwordx4 v[12:13], v[8:11], off
	ds_read_b32 v12, v209 offset:8896
	v_lshl_add_u64 v[14:15], v[72:73], 0, v[200:201]
	v_cvt_pk_bf16_f32 v8, v4, v5
	v_lshlrev_b64 v[14:15], 1, v[14:15]
	v_cvt_pk_bf16_f32 v9, v6, v7
	s_waitcnt lgkmcnt(0)
	v_pk_mul_f32 v[4:5], v[4:5], v[12:13] op_sel_hi:[1,0]
	v_cvt_pk_bf16_f32 v10, v0, v1
	v_cvt_pk_bf16_f32 v11, v2, v3
	v_lshl_add_u64 v[16:17], s[8:9], 0, v[14:15]
	v_pk_mul_f32 v[4:5], v[226:227], v[4:5]
	v_pk_mul_f32 v[2:3], v[2:3], v[12:13] op_sel_hi:[1,0]
	v_pk_mul_f32 v[0:1], v[0:1], v[12:13] op_sel_hi:[1,0]
	global_store_dwordx4 v[16:17], v[8:11], off nt
	v_pk_mul_f32 v[6:7], v[6:7], v[12:13] op_sel_hi:[1,0]
	s_nop 0
	v_pk_mul_f32 v[8:9], v[232:233], v[2:3]
	v_pk_mul_f32 v[2:3], v[230:231], v[0:1]
	v_cvt_pk_bf16_f32 v0, v4, v5
	v_lshl_add_u64 v[4:5], s[10:11], 0, v[14:15]
	v_pk_mul_f32 v[6:7], v[228:229], v[6:7]
	s_nop 0
	v_cvt_pk_bf16_f32 v1, v6, v7
	v_cvt_pk_bf16_f32 v2, v2, v3
	v_cvt_pk_bf16_f32 v3, v8, v9
	global_store_dwordx4 v[4:5], v[0:3], off

.LBB0_1000:
	s_or_b64 exec, exec, s[10:11]
	s_waitcnt lgkmcnt(0)
	s_barrier
	s_waitcnt lgkmcnt(0)
	v_lshl_add_u64 v[202:203], v[200:201], 2, s[34:35]
	global_load_dwordx4 v[196:199], v[202:203], off
	global_load_dwordx4 v[192:195], v[202:203], off offset:16
	global_load_dwordx4 v[236:239], v[202:203], off offset:512
	global_load_dwordx4 v[240:243], v[202:203], off offset:528
	v_lshl_add_u32 v206, v204, 2, 0
	ds_read_b32 v224, v206 offset:8192
	s_waitcnt vmcnt(2)
	v_lshlrev_b32_e32 v208, 16, v188
	v_and_b32_e32 v209, 0xffff0000, v188
	v_lshlrev_b32_e32 v210, 16, v189
	v_and_b32_e32 v211, 0xffff0000, v189
	s_waitcnt lgkmcnt(0)
	v_pk_mul_f32 v[126:127], v[126:127], v[224:225] op_sel_hi:[1,0]
	v_pk_mul_f32 v[124:125], v[124:125], v[224:225] op_sel_hi:[1,0]
	v_lshlrev_b32_e32 v212, 16, v190
	v_and_b32_e32 v213, 0xffff0000, v190
	v_lshlrev_b32_e32 v190, 16, v191
	v_and_b32_e32 v191, 0xffff0000, v191
	v_pk_mul_f32 v[122:123], v[122:123], v[224:225] op_sel_hi:[1,0]
	v_pk_mul_f32 v[120:121], v[120:121], v[224:225] op_sel_hi:[1,0]
	v_add_u32_e32 v204, s26, v204
	v_add_u32_e32 v226, 16, v204
	s_add_u32 s8, s18, 0x24800000
	v_ashrrev_i32_e32 v205, 31, v204
	v_ashrrev_i32_e32 v227, 31, v226
	s_addc_u32 s9, s19, 0
	v_lshlrev_b64 v[228:229], 11, v[204:205]
	v_lshlrev_b64 v[226:227], 11, v[226:227]
	v_lshlrev_b64 v[188:189], 1, v[200:201]
	v_lshl_add_u64 v[228:229], s[8:9], 0, v[228:229]
	v_lshlrev_b32_e32 v200, 16, v184
	v_and_b32_e32 v201, 0xffff0000, v184
	v_lshlrev_b32_e32 v184, 16, v185
	v_and_b32_e32 v185, 0xffff0000, v185
	v_lshlrev_b32_e32 v214, 16, v186
	v_and_b32_e32 v215, 0xffff0000, v186
	v_lshlrev_b32_e32 v186, 16, v187
	v_and_b32_e32 v187, 0xffff0000, v187
	v_lshlrev_b32_e32 v216, 16, v180
	v_and_b32_e32 v217, 0xffff0000, v180
	v_lshlrev_b32_e32 v180, 16, v181
	v_and_b32_e32 v181, 0xffff0000, v181
	v_lshlrev_b32_e32 v218, 16, v182
	v_and_b32_e32 v219, 0xffff0000, v182
	v_lshlrev_b32_e32 v182, 16, v183
	v_and_b32_e32 v183, 0xffff0000, v183
	v_lshlrev_b32_e32 v220, 16, v176
	v_and_b32_e32 v221, 0xffff0000, v176
	v_lshlrev_b32_e32 v222, 16, v178
	v_and_b32_e32 v223, 0xffff0000, v178
	v_lshlrev_b32_e32 v176, 16, v177
	v_and_b32_e32 v177, 0xffff0000, v177
	v_lshlrev_b32_e32 v178, 16, v179
	v_and_b32_e32 v179, 0xffff0000, v179
	v_pk_fma_f32 v[124:125], v[196:197], v[124:125], v[208:209]
	v_pk_fma_f32 v[126:127], v[198:199], v[126:127], v[210:211]
	v_pk_fma_f32 v[120:121], v[192:193], v[120:121], v[212:213]
	v_pk_fma_f32 v[122:123], v[194:195], v[122:123], v[190:191]
	v_cvt_pk_bf16_f32 v124, v124, v125
	v_cvt_pk_bf16_f32 v125, v126, v127
	v_cvt_pk_bf16_f32 v126, v120, v121
	v_lshl_add_u64 v[120:121], s[8:9], 0, v[226:227]
	v_cvt_pk_bf16_f32 v127, v122, v123
	ds_read_b32 v190, v206 offset:8256
	v_lshl_add_u64 v[122:123], v[228:229], 0, v[188:189]
	v_lshl_add_u64 v[120:121], v[120:121], 0, v[188:189]
	global_store_dwordx4 v[122:123], v[124:127], off
	s_waitcnt lgkmcnt(0)
	v_pk_mul_f32 v[118:119], v[118:119], v[190:191] op_sel_hi:[1,0]
	v_pk_mul_f32 v[116:117], v[116:117], v[190:191] op_sel_hi:[1,0]
	v_pk_mul_f32 v[114:115], v[114:115], v[190:191] op_sel_hi:[1,0]
	v_pk_mul_f32 v[112:113], v[112:113], v[190:191] op_sel_hi:[1,0]
	v_pk_fma_f32 v[116:117], v[196:197], v[116:117], v[200:201]
	v_pk_fma_f32 v[118:119], v[198:199], v[118:119], v[184:185]
	v_pk_fma_f32 v[124:125], v[192:193], v[112:113], v[214:215]
	v_pk_fma_f32 v[126:127], v[194:195], v[114:115], v[186:187]
	v_cvt_pk_bf16_f32 v112, v116, v117
	v_cvt_pk_bf16_f32 v113, v118, v119
	v_cvt_pk_bf16_f32 v114, v124, v125
	v_add_u32_e32 v116, 48, v204
	v_cvt_pk_bf16_f32 v115, v126, v127
	global_store_dwordx4 v[120:121], v[112:115], off
	ds_read_b32 v112, v206 offset:8320
	v_ashrrev_i32_e32 v117, 31, v116
	v_add_u32_e32 v114, 32, v204
	v_ashrrev_i32_e32 v115, 31, v114
	s_waitcnt lgkmcnt(0)
	v_pk_mul_f32 v[110:111], v[110:111], v[112:113] op_sel_hi:[1,0]
	v_pk_mul_f32 v[108:109], v[108:109], v[112:113] op_sel_hi:[1,0]
	v_pk_mul_f32 v[106:107], v[106:107], v[112:113] op_sel_hi:[1,0]
	v_pk_mul_f32 v[104:105], v[104:105], v[112:113] op_sel_hi:[1,0]
	v_pk_fma_f32 v[108:109], v[196:197], v[108:109], v[216:217]
	v_pk_fma_f32 v[110:111], v[198:199], v[110:111], v[180:181]
	v_pk_fma_f32 v[104:105], v[192:193], v[104:105], v[218:219]
	v_pk_fma_f32 v[112:113], v[194:195], v[106:107], v[182:183]
	v_cvt_pk_bf16_f32 v106, v108, v109
	v_cvt_pk_bf16_f32 v107, v110, v111
	v_cvt_pk_bf16_f32 v108, v104, v105
	v_lshlrev_b64 v[104:105], 11, v[114:115]
	v_cvt_pk_bf16_f32 v109, v112, v113
	ds_read_b32 v110, v206 offset:8384
	v_lshl_add_u64 v[104:105], s[8:9], 0, v[104:105]
	v_lshl_add_u64 v[104:105], v[104:105], 0, v[188:189]
	global_store_dwordx4 v[104:105], v[106:109], off
	s_waitcnt lgkmcnt(0)
	v_pk_mul_f32 v[100:101], v[100:101], v[110:111] op_sel_hi:[1,0]
	v_pk_mul_f32 v[96:97], v[96:97], v[110:111] op_sel_hi:[1,0]
	v_pk_mul_f32 v[102:103], v[102:103], v[110:111] op_sel_hi:[1,0]
	v_pk_fma_f32 v[100:101], v[196:197], v[100:101], v[220:221]
	v_pk_mul_f32 v[98:99], v[98:99], v[110:111] op_sel_hi:[1,0]
	v_pk_fma_f32 v[96:97], v[192:193], v[96:97], v[222:223]
	v_pk_fma_f32 v[102:103], v[198:199], v[102:103], v[176:177]
	v_pk_fma_f32 v[106:107], v[194:195], v[98:99], v[178:179]
	v_cvt_pk_bf16_f32 v98, v100, v101
	v_cvt_pk_bf16_f32 v99, v102, v103
	v_cvt_pk_bf16_f32 v100, v96, v97
	v_lshlrev_b64 v[96:97], 11, v[116:117]
	v_lshl_add_u64 v[96:97], s[8:9], 0, v[96:97]
	v_lshl_add_u64 v[96:97], v[96:97], 0, v[188:189]
	v_cvt_pk_bf16_f32 v101, v106, v107
	global_store_dwordx4 v[96:97], v[98:101], off
	ds_read_b32 v98, v206 offset:8704
	v_lshlrev_b32_e32 v102, 16, v172
	v_add_u32_e32 v100, 0x80, v204
	v_and_b32_e32 v103, 0xffff0000, v172
	v_lshlrev_b32_e32 v108, 16, v174
	v_and_b32_e32 v109, 0xffff0000, v174
	s_waitcnt lgkmcnt(0)
	v_pk_mul_f32 v[92:93], v[92:93], v[98:99] op_sel_hi:[1,0]
	v_pk_mul_f32 v[88:89], v[88:89], v[98:99] op_sel_hi:[1,0]
	v_ashrrev_i32_e32 v101, 31, v100
	v_lshlrev_b32_e32 v106, 16, v173
	v_and_b32_e32 v107, 0xffff0000, v173
	v_lshlrev_b32_e32 v110, 16, v175
	v_and_b32_e32 v111, 0xffff0000, v175
	v_pk_mul_f32 v[94:95], v[94:95], v[98:99] op_sel_hi:[1,0]
	v_pk_fma_f32 v[92:93], v[196:197], v[92:93], v[102:103]
	v_pk_mul_f32 v[90:91], v[90:91], v[98:99] op_sel_hi:[1,0]
	v_pk_fma_f32 v[88:89], v[192:193], v[88:89], v[108:109]
	v_pk_fma_f32 v[94:95], v[198:199], v[94:95], v[106:107]
	v_pk_fma_f32 v[98:99], v[194:195], v[90:91], v[110:111]
	v_cvt_pk_bf16_f32 v90, v92, v93
	v_cvt_pk_bf16_f32 v91, v94, v95
	v_cvt_pk_bf16_f32 v92, v88, v89
	v_lshlrev_b64 v[88:89], 11, v[100:101]
	v_lshl_add_u64 v[88:89], s[8:9], 0, v[88:89]
	v_lshl_add_u64 v[88:89], v[88:89], 0, v[188:189]
	v_cvt_pk_bf16_f32 v93, v98, v99
	global_store_dwordx4 v[88:89], v[90:93], off
	ds_read_b32 v90, v206 offset:8768
	v_lshlrev_b32_e32 v94, 16, v168
	v_add_u32_e32 v92, 0x90, v204
	v_and_b32_e32 v95, 0xffff0000, v168
	v_lshlrev_b32_e32 v100, 16, v170
	v_and_b32_e32 v101, 0xffff0000, v170
	s_waitcnt lgkmcnt(0)
	v_pk_mul_f32 v[84:85], v[84:85], v[90:91] op_sel_hi:[1,0]
	v_pk_mul_f32 v[80:81], v[80:81], v[90:91] op_sel_hi:[1,0]
	v_ashrrev_i32_e32 v93, 31, v92
	v_lshlrev_b32_e32 v98, 16, v169
	v_and_b32_e32 v99, 0xffff0000, v169
	v_lshlrev_b32_e32 v102, 16, v171
	v_and_b32_e32 v103, 0xffff0000, v171
	v_pk_mul_f32 v[86:87], v[86:87], v[90:91] op_sel_hi:[1,0]
	v_pk_fma_f32 v[84:85], v[196:197], v[84:85], v[94:95]
	v_pk_mul_f32 v[82:83], v[82:83], v[90:91] op_sel_hi:[1,0]
	v_pk_fma_f32 v[80:81], v[192:193], v[80:81], v[100:101]
	v_pk_fma_f32 v[86:87], v[198:199], v[86:87], v[98:99]
	v_pk_fma_f32 v[90:91], v[194:195], v[82:83], v[102:103]
	v_cvt_pk_bf16_f32 v82, v84, v85
	v_cvt_pk_bf16_f32 v83, v86, v87
	v_cvt_pk_bf16_f32 v84, v80, v81
	v_lshlrev_b64 v[80:81], 11, v[92:93]
	v_lshl_add_u64 v[80:81], s[8:9], 0, v[80:81]
	v_lshl_add_u64 v[80:81], v[80:81], 0, v[188:189]
	v_cvt_pk_bf16_f32 v85, v90, v91
	global_store_dwordx4 v[80:81], v[82:85], off
	ds_read_b32 v82, v206 offset:8832
	v_lshlrev_b32_e32 v86, 16, v164
	v_add_u32_e32 v84, 0xa0, v204
	v_and_b32_e32 v87, 0xffff0000, v164
	v_lshlrev_b32_e32 v92, 16, v166
	v_and_b32_e32 v93, 0xffff0000, v166
	s_waitcnt lgkmcnt(0)
	v_pk_mul_f32 v[76:77], v[76:77], v[82:83] op_sel_hi:[1,0]
	v_pk_mul_f32 v[72:73], v[72:73], v[82:83] op_sel_hi:[1,0]
	v_ashrrev_i32_e32 v85, 31, v84
	v_lshlrev_b32_e32 v90, 16, v165
	v_and_b32_e32 v91, 0xffff0000, v165
	v_lshlrev_b32_e32 v94, 16, v167
	v_and_b32_e32 v95, 0xffff0000, v167
	v_pk_mul_f32 v[78:79], v[78:79], v[82:83] op_sel_hi:[1,0]
	v_pk_fma_f32 v[76:77], v[196:197], v[76:77], v[86:87]
	v_pk_mul_f32 v[74:75], v[74:75], v[82:83] op_sel_hi:[1,0]
	v_pk_fma_f32 v[72:73], v[192:193], v[72:73], v[92:93]
	v_pk_fma_f32 v[78:79], v[198:199], v[78:79], v[90:91]
	v_pk_fma_f32 v[82:83], v[194:195], v[74:75], v[94:95]
	v_cvt_pk_bf16_f32 v74, v76, v77
	v_cvt_pk_bf16_f32 v75, v78, v79
	v_cvt_pk_bf16_f32 v76, v72, v73
	v_lshlrev_b64 v[72:73], 11, v[84:85]
	v_lshl_add_u64 v[72:73], s[8:9], 0, v[72:73]
	v_lshl_add_u64 v[72:73], v[72:73], 0, v[188:189]
	v_cvt_pk_bf16_f32 v77, v82, v83
	global_store_dwordx4 v[72:73], v[74:77], off
	ds_read_b32 v74, v206 offset:8896
	v_lshlrev_b32_e32 v78, 16, v160
	v_add_u32_e32 v76, 0xb0, v204
	v_and_b32_e32 v79, 0xffff0000, v160
	v_ashrrev_i32_e32 v77, 31, v76
	s_waitcnt lgkmcnt(0)
	v_pk_mul_f32 v[68:69], v[68:69], v[74:75] op_sel_hi:[1,0]
	v_lshlrev_b32_e32 v84, 16, v162
	v_and_b32_e32 v85, 0xffff0000, v162
	v_pk_fma_f32 v[68:69], v[196:197], v[68:69], v[78:79]
	v_pk_mul_f32 v[64:65], v[64:65], v[74:75] op_sel_hi:[1,0]
	v_pk_mul_f32 v[70:71], v[70:71], v[74:75] op_sel_hi:[1,0]
	v_pk_mul_f32 v[66:67], v[66:67], v[74:75] op_sel_hi:[1,0]
	v_pk_fma_f32 v[74:75], v[192:193], v[64:65], v[84:85]
	v_cvt_pk_bf16_f32 v64, v68, v69
	v_lshlrev_b64 v[68:69], 11, v[76:77]
	v_lshlrev_b32_e32 v82, 16, v161
	v_and_b32_e32 v83, 0xffff0000, v161
	v_lshlrev_b32_e32 v86, 16, v163
	v_and_b32_e32 v87, 0xffff0000, v163
	v_lshl_add_u64 v[68:69], s[8:9], 0, v[68:69]
	v_pk_fma_f32 v[70:71], v[198:199], v[70:71], v[82:83]
	v_pk_fma_f32 v[78:79], v[194:195], v[66:67], v[86:87]
	v_cvt_pk_bf16_f32 v65, v70, v71
	v_cvt_pk_bf16_f32 v66, v74, v75
	v_lshl_add_u64 v[74:75], v[68:69], 0, v[188:189]
	v_cvt_pk_bf16_f32 v67, v78, v79
	global_store_dwordx4 v[74:75], v[64:67], off
	ds_read_b32 v76, v206 offset:8192
	v_lshlrev_b32_e32 v78, 16, v156
	v_and_b32_e32 v79, 0xffff0000, v156
	v_lshlrev_b32_e32 v84, 16, v158
	v_and_b32_e32 v85, 0xffff0000, v158
	s_waitcnt lgkmcnt(0)
	v_pk_mul_f32 v[60:61], v[60:61], v[76:77] op_sel_hi:[1,0]
	v_pk_mul_f32 v[56:57], v[56:57], v[76:77] op_sel_hi:[1,0]
	v_lshlrev_b32_e32 v82, 16, v157
	v_and_b32_e32 v83, 0xffff0000, v157
	v_lshlrev_b32_e32 v86, 16, v159
	v_and_b32_e32 v87, 0xffff0000, v159
	v_pk_mul_f32 v[62:63], v[62:63], v[76:77] op_sel_hi:[1,0]
	v_pk_mul_f32 v[58:59], v[58:59], v[76:77] op_sel_hi:[1,0]
	s_waitcnt vmcnt(8)
	v_pk_fma_f32 v[60:61], v[236:237], v[60:61], v[78:79]
	v_pk_fma_f32 v[76:77], v[240:241], v[56:57], v[84:85]
	v_cvt_pk_bf16_f32 v56, v60, v61
	v_pk_fma_f32 v[62:63], v[238:239], v[62:63], v[82:83]
	v_pk_fma_f32 v[78:79], v[242:243], v[58:59], v[86:87]
	v_cvt_pk_bf16_f32 v57, v62, v63
	v_cvt_pk_bf16_f32 v58, v76, v77
	v_lshlrev_b32_e32 v60, 16, v153
	v_cvt_pk_bf16_f32 v59, v78, v79
	global_store_dwordx4 v[122:123], v[56:59], off offset:256
	ds_read_b32 v56, v206 offset:8256
	v_and_b32_e32 v61, 0xffff0000, v153
	v_lshlrev_b32_e32 v58, 16, v152
	v_and_b32_e32 v59, 0xffff0000, v152
	v_lshlrev_b32_e32 v62, 16, v154
	v_and_b32_e32 v63, 0xffff0000, v154
	v_lshlrev_b32_e32 v76, 16, v155
	v_and_b32_e32 v77, 0xffff0000, v155
	s_waitcnt lgkmcnt(0)
	v_pk_mul_f32 v[54:55], v[54:55], v[56:57] op_sel_hi:[1,0]
	v_pk_mul_f32 v[52:53], v[52:53], v[56:57] op_sel_hi:[1,0]
	v_pk_mul_f32 v[50:51], v[50:51], v[56:57] op_sel_hi:[1,0]
	v_pk_mul_f32 v[48:49], v[48:49], v[56:57] op_sel_hi:[1,0]
	v_pk_fma_f32 v[52:53], v[236:237], v[52:53], v[58:59]
	v_pk_fma_f32 v[54:55], v[238:239], v[54:55], v[60:61]
	v_pk_fma_f32 v[56:57], v[240:241], v[48:49], v[62:63]
	v_pk_fma_f32 v[58:59], v[242:243], v[50:51], v[76:77]
	v_cvt_pk_bf16_f32 v48, v52, v53
	v_cvt_pk_bf16_f32 v49, v54, v55
	v_cvt_pk_bf16_f32 v50, v56, v57
	v_lshlrev_b32_e32 v54, 16, v150
	v_cvt_pk_bf16_f32 v51, v58, v59
	global_store_dwordx4 v[120:121], v[48:51], off offset:256
	ds_read_b32 v48, v206 offset:8320
	v_and_b32_e32 v55, 0xffff0000, v150
	v_lshlrev_b32_e32 v50, 16, v148
	v_and_b32_e32 v51, 0xffff0000, v148
	v_lshlrev_b32_e32 v52, 16, v149
	s_waitcnt lgkmcnt(0)
	v_pk_mul_f32 v[44:45], v[44:45], v[48:49] op_sel_hi:[1,0]
	v_pk_mul_f32 v[40:41], v[40:41], v[48:49] op_sel_hi:[1,0]
	v_and_b32_e32 v53, 0xffff0000, v149
	v_lshlrev_b32_e32 v56, 16, v151
	v_and_b32_e32 v57, 0xffff0000, v151
	v_pk_mul_f32 v[46:47], v[46:47], v[48:49] op_sel_hi:[1,0]
	v_pk_fma_f32 v[44:45], v[236:237], v[44:45], v[50:51]
	v_pk_mul_f32 v[42:43], v[42:43], v[48:49] op_sel_hi:[1,0]
	v_pk_fma_f32 v[48:49], v[240:241], v[40:41], v[54:55]
	v_cvt_pk_bf16_f32 v40, v44, v45
	v_pk_fma_f32 v[46:47], v[238:239], v[46:47], v[52:53]
	v_pk_fma_f32 v[50:51], v[242:243], v[42:43], v[56:57]
	v_cvt_pk_bf16_f32 v41, v46, v47
	v_cvt_pk_bf16_f32 v42, v48, v49
	v_lshlrev_b32_e32 v44, 16, v145
	v_cvt_pk_bf16_f32 v43, v50, v51
	global_store_dwordx4 v[104:105], v[40:43], off offset:256
	ds_read_b32 v40, v206 offset:8384
	v_and_b32_e32 v45, 0xffff0000, v145
	v_lshlrev_b32_e32 v42, 16, v144
	v_and_b32_e32 v43, 0xffff0000, v144
	v_lshlrev_b32_e32 v46, 16, v146
	v_and_b32_e32 v47, 0xffff0000, v146
	v_lshlrev_b32_e32 v48, 16, v147
	v_and_b32_e32 v49, 0xffff0000, v147
	s_waitcnt lgkmcnt(0)
	v_pk_mul_f32 v[38:39], v[38:39], v[40:41] op_sel_hi:[1,0]
	v_pk_mul_f32 v[36:37], v[36:37], v[40:41] op_sel_hi:[1,0]
	v_pk_mul_f32 v[34:35], v[34:35], v[40:41] op_sel_hi:[1,0]
	v_pk_mul_f32 v[32:33], v[32:33], v[40:41] op_sel_hi:[1,0]
	v_pk_fma_f32 v[36:37], v[236:237], v[36:37], v[42:43]
	v_pk_fma_f32 v[38:39], v[238:239], v[38:39], v[44:45]
	v_pk_fma_f32 v[40:41], v[240:241], v[32:33], v[46:47]
	v_pk_fma_f32 v[42:43], v[242:243], v[34:35], v[48:49]
	v_cvt_pk_bf16_f32 v32, v36, v37
	v_cvt_pk_bf16_f32 v33, v38, v39
	v_cvt_pk_bf16_f32 v34, v40, v41
	v_lshlrev_b32_e32 v38, 16, v142
	v_cvt_pk_bf16_f32 v35, v42, v43
	global_store_dwordx4 v[96:97], v[32:35], off offset:256
	ds_read_b32 v32, v206 offset:8704
	v_and_b32_e32 v39, 0xffff0000, v142
	v_lshlrev_b32_e32 v34, 16, v140
	v_and_b32_e32 v35, 0xffff0000, v140
	v_lshlrev_b32_e32 v36, 16, v141
	s_waitcnt lgkmcnt(0)
	v_pk_mul_f32 v[28:29], v[28:29], v[32:33] op_sel_hi:[1,0]
	v_pk_mul_f32 v[24:25], v[24:25], v[32:33] op_sel_hi:[1,0]
	v_and_b32_e32 v37, 0xffff0000, v141
	v_lshlrev_b32_e32 v40, 16, v143
	v_and_b32_e32 v41, 0xffff0000, v143
	v_pk_mul_f32 v[30:31], v[30:31], v[32:33] op_sel_hi:[1,0]
	v_pk_fma_f32 v[28:29], v[236:237], v[28:29], v[34:35]
	v_pk_mul_f32 v[26:27], v[26:27], v[32:33] op_sel_hi:[1,0]
	v_pk_fma_f32 v[32:33], v[240:241], v[24:25], v[38:39]
	v_cvt_pk_bf16_f32 v24, v28, v29
	v_pk_fma_f32 v[30:31], v[238:239], v[30:31], v[36:37]
	v_pk_fma_f32 v[34:35], v[242:243], v[26:27], v[40:41]
	v_cvt_pk_bf16_f32 v25, v30, v31
	v_cvt_pk_bf16_f32 v26, v32, v33
	v_lshlrev_b32_e32 v28, 16, v137
	v_cvt_pk_bf16_f32 v27, v34, v35
	global_store_dwordx4 v[88:89], v[24:27], off offset:256
	ds_read_b32 v24, v206 offset:8768
	v_and_b32_e32 v29, 0xffff0000, v137
	v_lshlrev_b32_e32 v26, 16, v136
	v_and_b32_e32 v27, 0xffff0000, v136
	v_lshlrev_b32_e32 v30, 16, v138
	v_and_b32_e32 v31, 0xffff0000, v138
	v_lshlrev_b32_e32 v32, 16, v139
	v_and_b32_e32 v33, 0xffff0000, v139
	s_waitcnt lgkmcnt(0)
	v_pk_mul_f32 v[22:23], v[22:23], v[24:25] op_sel_hi:[1,0]
	v_pk_mul_f32 v[20:21], v[20:21], v[24:25] op_sel_hi:[1,0]
	v_pk_mul_f32 v[18:19], v[18:19], v[24:25] op_sel_hi:[1,0]
	v_pk_mul_f32 v[16:17], v[16:17], v[24:25] op_sel_hi:[1,0]
	v_pk_fma_f32 v[20:21], v[236:237], v[20:21], v[26:27]
	v_pk_fma_f32 v[22:23], v[238:239], v[22:23], v[28:29]
	v_pk_fma_f32 v[24:25], v[240:241], v[16:17], v[30:31]
	v_pk_fma_f32 v[26:27], v[242:243], v[18:19], v[32:33]
	v_cvt_pk_bf16_f32 v16, v20, v21
	v_cvt_pk_bf16_f32 v17, v22, v23
	v_cvt_pk_bf16_f32 v18, v24, v25
	v_lshlrev_b32_e32 v22, 16, v134
	v_cvt_pk_bf16_f32 v19, v26, v27
	global_store_dwordx4 v[80:81], v[16:19], off offset:256
	ds_read_b32 v16, v206 offset:8832
	v_and_b32_e32 v23, 0xffff0000, v134
	v_lshlrev_b32_e32 v18, 16, v132
	v_and_b32_e32 v19, 0xffff0000, v132
	v_lshlrev_b32_e32 v20, 16, v133
	s_waitcnt lgkmcnt(0)
	v_pk_mul_f32 v[12:13], v[12:13], v[16:17] op_sel_hi:[1,0]
	v_pk_mul_f32 v[8:9], v[8:9], v[16:17] op_sel_hi:[1,0]
	v_and_b32_e32 v21, 0xffff0000, v133
	v_lshlrev_b32_e32 v24, 16, v135
	v_and_b32_e32 v25, 0xffff0000, v135
	v_pk_mul_f32 v[14:15], v[14:15], v[16:17] op_sel_hi:[1,0]
	v_pk_fma_f32 v[12:13], v[236:237], v[12:13], v[18:19]
	v_pk_mul_f32 v[10:11], v[10:11], v[16:17] op_sel_hi:[1,0]
	v_pk_fma_f32 v[16:17], v[240:241], v[8:9], v[22:23]
	v_cvt_pk_bf16_f32 v8, v12, v13
	v_pk_fma_f32 v[14:15], v[238:239], v[14:15], v[20:21]
	v_pk_fma_f32 v[18:19], v[242:243], v[10:11], v[24:25]
	v_cvt_pk_bf16_f32 v9, v14, v15
	v_cvt_pk_bf16_f32 v10, v16, v17
	v_lshlrev_b32_e32 v12, 16, v129
	v_cvt_pk_bf16_f32 v11, v18, v19
	global_store_dwordx4 v[72:73], v[8:11], off offset:256
	ds_read_b32 v8, v206 offset:8896
	v_and_b32_e32 v13, 0xffff0000, v129
	v_lshlrev_b32_e32 v10, 16, v128
	v_and_b32_e32 v11, 0xffff0000, v128
	v_lshlrev_b32_e32 v14, 16, v130
	v_and_b32_e32 v15, 0xffff0000, v130
	v_lshlrev_b32_e32 v16, 16, v131
	v_and_b32_e32 v17, 0xffff0000, v131
	s_waitcnt lgkmcnt(0)
	v_pk_mul_f32 v[6:7], v[6:7], v[8:9] op_sel_hi:[1,0]
	v_pk_mul_f32 v[4:5], v[4:5], v[8:9] op_sel_hi:[1,0]
	v_pk_mul_f32 v[2:3], v[2:3], v[8:9] op_sel_hi:[1,0]
	v_pk_mul_f32 v[0:1], v[0:1], v[8:9] op_sel_hi:[1,0]
	v_pk_fma_f32 v[4:5], v[236:237], v[4:5], v[10:11]
	v_pk_fma_f32 v[6:7], v[238:239], v[6:7], v[12:13]
	v_pk_fma_f32 v[8:9], v[240:241], v[0:1], v[14:15]
	v_pk_fma_f32 v[10:11], v[242:243], v[2:3], v[16:17]
	v_cvt_pk_bf16_f32 v0, v4, v5
	v_cvt_pk_bf16_f32 v1, v6, v7
	v_cvt_pk_bf16_f32 v2, v8, v9
	s_nop 0
	v_cvt_pk_bf16_f32 v3, v10, v11
	global_store_dwordx4 v[74:75], v[0:3], off offset:256
